# two L1 norm sweeps: the four x loads issued up front with counted vmcnt(3/2/1/0) (sum-of-squares temporaries renamed to v18/v19); on top of hoisted gain-vector loads in all six norm loops + serial-cha
# baseline (speedup 1.0000x reference)
; __device__ __forceinline__ void norm_row_f32(float* xrow, const float* g, int lane) {
;   f32x4* xr = (f32x4*)xrow + lane; const f32x4* gr = (const f32x4*)g + lane;
;   f32x4 v[4]; float s = 0.f;
; #pragma unroll
;   for (int j = 0; j < 4; ++j) { v[j] = xr[64 * j]; s += (v[j].x * v[j].x + v[j].y * v[j].y) + (v[j].z * v[j].z + v[j].w * v[j].w); }
;   const float rinv = 1.0f / sqrtf(wave_sum(s) * (1.f / DM) + EPSN);
; #pragma unroll
;   for (int j = 0; j < 4; ++j) { const f32x4 gg = gr[64 * j]; xr[64 * j] = v[j] * rinv * gg; }
; }
.LBB0_512:
	v_ashrrev_i32_e32 v23, 31, v22
	v_lshlrev_b64 v[2:3], 12, v[22:23]
	v_lshl_add_u64 v[28:29], v[24:25], 0, v[2:3]
	global_load_dwordx4 v[2:5], v[28:29], off
	global_load_dwordx4 v[6:9], v[28:29], off offset:1024
	global_load_dwordx4 v[10:13], v[28:29], off offset:2048
	global_load_dwordx4 v[14:17], v[28:29], off offset:3072
	v_add_u32_e32 v22, s94, v22
	s_waitcnt vmcnt(3)
	v_mul_f32_e32 v0, v3, v3
	v_mul_f32_e32 v18, v5, v5
	v_fmac_f32_e32 v0, v2, v2
	v_fmac_f32_e32 v18, v4, v4
	v_add_f32_e32 v0, v0, v18
	s_waitcnt vmcnt(2)
	v_mul_f32_e32 v18, v7, v7
	v_mul_f32_e32 v19, v9, v9
	v_fmac_f32_e32 v18, v6, v6
	v_fmac_f32_e32 v19, v8, v8
	v_add_f32_e32 v18, v18, v19
	v_add_f32_e32 v0, v0, v18
	s_waitcnt vmcnt(1)
	v_mul_f32_e32 v18, v11, v11
	v_mul_f32_e32 v19, v13, v13
	v_fmac_f32_e32 v18, v10, v10
	v_fmac_f32_e32 v19, v12, v12
	v_add_f32_e32 v18, v18, v19
	v_add_f32_e32 v0, v0, v18
	s_waitcnt vmcnt(0)
	v_mul_f32_e32 v18, v15, v15
	v_mul_f32_e32 v19, v17, v17
	v_fmac_f32_e32 v18, v14, v14
	v_fmac_f32_e32 v19, v16, v16
	v_add_f32_e32 v18, v18, v19
	v_add_f32_e32 v0, v0, v18
	ds_swizzle_b32 v18, v0 offset:swizzle(SWAP,1)
	s_waitcnt lgkmcnt(0)
	v_add_f32_e32 v0, v0, v18
	ds_swizzle_b32 v18, v0 offset:swizzle(SWAP,2)
	s_waitcnt lgkmcnt(0)
	v_add_f32_e32 v0, v0, v18
	ds_swizzle_b32 v18, v0 offset:swizzle(SWAP,4)
	s_waitcnt lgkmcnt(0)
	v_add_f32_e32 v0, v0, v18
	ds_swizzle_b32 v18, v0 offset:swizzle(SWAP,8)
	s_waitcnt lgkmcnt(0)
	v_add_f32_e32 v0, v0, v18
	ds_swizzle_b32 v18, v0 offset:swizzle(SWAP,16)
	s_waitcnt lgkmcnt(0)
	v_add_f32_e32 v0, v0, v18
	v_mov_b32_e32 v18, v0
	s_nop 1
	v_permlane32_swap_b32_e32 v0, v18
	v_add_f32_e32 v0, v0, v18
	v_fmamk_f32 v0, v0, 0x3a800000, v229
	v_cmp_gt_f32_e32 vcc, s87, v0
	v_mul_f32_e32 v18, 0x4f800000, v0
	s_nop 0
	v_cndmask_b32_e32 v0, v0, v18, vcc
	v_sqrt_f32_e32 v18, v0
	s_nop 0
	v_add_u32_e32 v19, -1, v18
	v_fma_f32 v20, -v19, v18, v0
	v_cmp_ge_f32_e64 s[38:39], 0, v20
	v_add_u32_e32 v20, 1, v18
	s_nop 0
	v_cndmask_b32_e64 v19, v18, v19, s[38:39]
	v_fma_f32 v18, -v20, v18, v0
	v_cmp_lt_f32_e64 s[38:39], 0, v18
	s_nop 1
	v_cndmask_b32_e64 v18, v19, v20, s[38:39]
	v_mul_f32_e32 v19, 0x37800000, v18
	v_cndmask_b32_e32 v18, v18, v19, vcc
	v_cmp_class_f32_e32 vcc, v0, v230
	s_nop 1
	v_cndmask_b32_e32 v0, v18, v0, vcc
	v_div_scale_f32 v18, s[0:1], v0, v0, 1.0
	v_rcp_f32_e32 v19, v18
	s_movk_i32 s0, 0x3fff
	v_fma_f32 v20, -v18, v19, 1.0
	v_fmac_f32_e32 v19, v20, v19
	v_div_scale_f32 v20, vcc, 1.0, v0, 1.0
	v_mul_f32_e32 v21, v20, v19
	v_fma_f32 v23, -v18, v21, v20
	v_fmac_f32_e32 v21, v23, v19
	v_fma_f32 v18, -v18, v21, v20
	v_div_fmas_f32 v18, v18, v19, v21
	v_div_fixup_f32 v0, v18, v0, 1.0
	global_load_dwordx4 v[18:21], v[26:27], off
	global_load_dwordx4 v[40:43], v[26:27], off offset:1024
	global_load_dwordx4 v[44:47], v[26:27], off offset:2048
	global_load_dwordx4 v[48:51], v[26:27], off offset:3072
	v_pk_mul_f32 v[2:3], v[2:3], v[0:1] op_sel_hi:[1,0]
	v_pk_mul_f32 v[4:5], v[4:5], v[0:1] op_sel_hi:[1,0]
	v_pk_mul_f32 v[8:9], v[8:9], v[0:1] op_sel_hi:[1,0]
	v_pk_mul_f32 v[6:7], v[6:7], v[0:1] op_sel_hi:[1,0]
	v_cmp_lt_i32_e32 vcc, s0, v22
	s_or_b64 s[24:25], vcc, s[24:25]
	s_waitcnt vmcnt(0)
	v_pk_mul_f32 v[4:5], v[20:21], v[4:5]
	v_pk_mul_f32 v[2:3], v[18:19], v[2:3]
	global_store_dwordx4 v[28:29], v[2:5], off
	s_nop 1
	v_pk_mul_f32 v[2:3], v[40:41], v[6:7]
	v_pk_mul_f32 v[4:5], v[42:43], v[8:9]
	global_store_dwordx4 v[28:29], v[2:5], off offset:1024
	v_pk_mul_f32 v[6:7], v[12:13], v[0:1] op_sel_hi:[1,0]
	v_pk_mul_f32 v[8:9], v[10:11], v[0:1] op_sel_hi:[1,0]
	v_pk_mul_f32 v[4:5], v[46:47], v[6:7]
	v_pk_mul_f32 v[2:3], v[44:45], v[8:9]
	global_store_dwordx4 v[28:29], v[2:5], off offset:2048
	v_pk_mul_f32 v[6:7], v[16:17], v[0:1] op_sel_hi:[1,0]
	v_pk_mul_f32 v[8:9], v[14:15], v[0:1] op_sel_hi:[1,0]
	v_pk_mul_f32 v[4:5], v[50:51], v[6:7]
	v_pk_mul_f32 v[2:3], v[48:49], v[8:9]
	global_store_dwordx4 v[28:29], v[2:5], off offset:3072
	s_andn2_b64 exec, exec, s[24:25]
	s_cbranch_execnz .LBB0_512

; __device__ __forceinline__ unsigned cvtpk(float lo, float hi) { unsigned r; asm volatile("v_cvt_pk_bf16_f32 %0, %1, %2" : "=v"(r) : "v"(lo), "v"(hi)); return r; }
; __device__ __forceinline__ void norm_row_bf16(const float* xrow, const float* g, bf16_t* orow, int lane) {
;   const f32x4* xr = (const f32x4*)xrow + lane; const f32x4* gr = (const f32x4*)g + lane;
;   f32x4 v[4]; float s = 0.f;
; #pragma unroll
;   for (int j = 0; j < 4; ++j) { v[j] = xr[64 * j]; s += (v[j].x * v[j].x + v[j].y * v[j].y) + (v[j].z * v[j].z + v[j].w * v[j].w); }
;   const float rinv = 1.0f / sqrtf(wave_sum(s) * (1.f / DM) + EPSN);
;   u32x2* o8 = (u32x2*)orow + lane;
; #pragma unroll
;   for (int j = 0; j < 4; ++j) { const f32x4 gg = gr[64 * j]; u32x2 w = {cvtpk(v[j].x * rinv * gg.x, v[j].y * rinv * gg.y), cvtpk(v[j].z * rinv * gg.z, v[j].w * rinv * gg.w)}; o8[64 * j] = w; }
; }
.LBB0_517:
	v_ashrrev_i32_e32 v23, 31, v22
	v_lshlrev_b64 v[2:3], 12, v[22:23]
	v_lshl_add_u64 v[6:7], v[24:25], 0, v[2:3]
	global_load_dwordx4 v[14:17], v[6:7], off
	global_load_dwordx4 v[10:13], v[6:7], off offset:1024
	global_load_dwordx4 v[2:5], v[6:7], off offset:2048
	global_load_dwordx4 v[6:9], v[6:7], off offset:3072
	s_waitcnt vmcnt(3)
	v_mul_f32_e32 v0, v15, v15
	v_mul_f32_e32 v18, v17, v17
	v_fmac_f32_e32 v0, v14, v14
	v_fmac_f32_e32 v18, v16, v16
	v_add_f32_e32 v0, v0, v18
	s_waitcnt vmcnt(2)
	v_mul_f32_e32 v18, v11, v11
	v_mul_f32_e32 v19, v13, v13
	v_fmac_f32_e32 v18, v10, v10
	v_fmac_f32_e32 v19, v12, v12
	v_add_f32_e32 v18, v18, v19
	v_add_f32_e32 v0, v0, v18
	s_waitcnt vmcnt(1)
	v_mul_f32_e32 v18, v3, v3
	v_mul_f32_e32 v19, v5, v5
	v_fmac_f32_e32 v18, v2, v2
	v_fmac_f32_e32 v19, v4, v4
	v_add_f32_e32 v18, v18, v19
	v_add_f32_e32 v0, v0, v18
	s_waitcnt vmcnt(0)
	v_mul_f32_e32 v18, v7, v7
	v_mul_f32_e32 v19, v9, v9
	v_fmac_f32_e32 v18, v6, v6
	v_fmac_f32_e32 v19, v8, v8
	v_add_f32_e32 v18, v18, v19
	v_add_f32_e32 v0, v0, v18
	ds_swizzle_b32 v18, v0 offset:swizzle(SWAP,1)
	s_waitcnt lgkmcnt(0)
	v_add_f32_e32 v0, v0, v18
	ds_swizzle_b32 v18, v0 offset:swizzle(SWAP,2)
	s_waitcnt lgkmcnt(0)
	v_add_f32_e32 v0, v0, v18
	ds_swizzle_b32 v18, v0 offset:swizzle(SWAP,4)
	s_waitcnt lgkmcnt(0)
	v_add_f32_e32 v0, v0, v18
	ds_swizzle_b32 v18, v0 offset:swizzle(SWAP,8)
	s_waitcnt lgkmcnt(0)
	v_add_f32_e32 v0, v0, v18
	ds_swizzle_b32 v18, v0 offset:swizzle(SWAP,16)
	s_waitcnt lgkmcnt(0)
	v_add_f32_e32 v0, v0, v18
	v_mov_b32_e32 v18, v0
	s_nop 1
	v_permlane32_swap_b32_e32 v0, v18
	v_add_f32_e32 v0, v0, v18
	v_fmamk_f32 v0, v0, 0x3a800000, v229
	v_cmp_gt_f32_e32 vcc, s87, v0
	v_mul_f32_e32 v18, 0x4f800000, v0
	s_nop 0
	v_cndmask_b32_e32 v0, v0, v18, vcc
	v_sqrt_f32_e32 v18, v0
	s_nop 0
	v_add_u32_e32 v19, -1, v18
	v_fma_f32 v20, -v19, v18, v0
	v_cmp_ge_f32_e64 s[38:39], 0, v20
	v_add_u32_e32 v20, 1, v18
	s_nop 0
	v_cndmask_b32_e64 v19, v18, v19, s[38:39]
	v_fma_f32 v18, -v20, v18, v0
	v_cmp_lt_f32_e64 s[38:39], 0, v18
	s_nop 1
	v_cndmask_b32_e64 v18, v19, v20, s[38:39]
	v_mul_f32_e32 v19, 0x37800000, v18
	v_cndmask_b32_e32 v18, v18, v19, vcc
	v_cmp_class_f32_e32 vcc, v0, v230
	s_nop 1
	v_cndmask_b32_e32 v0, v18, v0, vcc
	v_div_scale_f32 v18, s[0:1], v0, v0, 1.0
	v_rcp_f32_e32 v19, v18
	s_movk_i32 s0, 0x7fff
	v_fma_f32 v20, -v18, v19, 1.0
	v_fmac_f32_e32 v19, v20, v19
	v_div_scale_f32 v20, vcc, 1.0, v0, 1.0
	v_mul_f32_e32 v21, v20, v19
	v_fma_f32 v30, -v18, v21, v20
	v_fmac_f32_e32 v21, v30, v19
	v_fma_f32 v18, -v18, v21, v20
	v_div_fmas_f32 v18, v18, v19, v21
	v_div_fixup_f32 v0, v18, v0, 1.0
	v_lshlrev_b64 v[18:19], 11, v[22:23]
	v_lshl_add_u64 v[30:31], v[28:29], 0, v[18:19]
	global_load_dwordx4 v[18:21], v[26:27], off
	global_load_dwordx4 v[40:43], v[26:27], off offset:1024
	global_load_dwordx4 v[44:47], v[26:27], off offset:2048
	global_load_dwordx4 v[48:51], v[26:27], off offset:3072
	v_mul_f32_e32 v14, v14, v0
	v_mul_f32_e32 v15, v15, v0
	v_mul_f32_e32 v10, v10, v0
	v_mul_f32_e32 v11, v11, v0
	v_mul_f32_e32 v2, v2, v0
	v_mul_f32_e32 v3, v3, v0
	v_mul_f32_e32 v6, v6, v0
	v_add_u32_e32 v22, s94, v22
	v_cmp_lt_i32_e32 vcc, s0, v22
	s_or_b64 s[24:25], vcc, s[24:25]
	s_waitcnt vmcnt(0)
	v_mul_f32_e32 v14, v18, v14
	v_mul_f32_e32 v15, v19, v15
	v_cvt_pk_bf16_f32 v14, v14, v15
	v_mul_f32_e32 v15, v16, v0
	v_mul_f32_e32 v15, v20, v15
	v_mul_f32_e32 v16, v17, v0
	v_mul_f32_e32 v16, v21, v16
	v_cvt_pk_bf16_f32 v15, v15, v16
	global_store_dwordx2 v[30:31], v[14:15], off
	v_mul_f32_e32 v10, v40, v10
	v_mul_f32_e32 v11, v41, v11
	v_cvt_pk_bf16_f32 v10, v10, v11
	v_mul_f32_e32 v11, v12, v0
	v_mul_f32_e32 v11, v42, v11
	v_mul_f32_e32 v12, v13, v0
	v_mul_f32_e32 v12, v43, v12
	v_cvt_pk_bf16_f32 v11, v11, v12
	global_store_dwordx2 v[30:31], v[10:11], off offset:512
	v_mul_f32_e32 v2, v2, v44
	v_mul_f32_e32 v3, v3, v45
	v_cvt_pk_bf16_f32 v2, v2, v3
	v_mul_f32_e32 v3, v4, v0
	v_mul_f32_e32 v3, v3, v46
	v_mul_f32_e32 v4, v5, v0
	v_mul_f32_e32 v4, v4, v47
	v_cvt_pk_bf16_f32 v3, v3, v4
	global_store_dwordx2 v[30:31], v[2:3], off offset:1024
	v_mul_f32_e32 v2, v6, v48
	v_mul_f32_e32 v6, v7, v0
	v_mul_f32_e32 v3, v6, v49
	v_cvt_pk_bf16_f32 v2, v2, v3
	v_mul_f32_e32 v3, v8, v0
	v_mul_f32_e32 v3, v3, v50
	v_mul_f32_e32 v0, v9, v0
	v_mul_f32_e32 v0, v0, v51
	v_cvt_pk_bf16_f32 v3, v3, v0
	global_store_dwordx2 v[30:31], v[2:3], off offset:1536
	s_andn2_b64 exec, exec, s[24:25]
	s_cbranch_execnz .LBB0_517
